# NSA selected loop: selection bitmap words read once into registers before the loop instead of one LDS read per tile iteration
# baseline (speedup 1.0000x reference)
.LBB0_1646:
	s_and_saveexec_b64 s[0:1], vcc
	v_lshl_add_u32 v0, v6, 4, 0
	v_add_u32_e32 v0, 0x11200, v0
	ds_write_b128 v0, v[2:5]
	s_or_b64 exec, exec, s[0:1]
	s_mul_i32 s94, s20, 0x2c00000
	v_mov_b32_e32 v0, v1
	s_waitcnt lgkmcnt(0)
	s_barrier
	s_add_u32 s74, s18, s94
	s_getreg_b32 s0, hwreg(HW_REG_HW_ID, 0, 6)
	s_addc_u32 s75, s19, 0
	s_lshl_b32 s0, s0, 2
	s_and_b32 s0, s0, 0xfc
	v_add_u32_e32 v2, s0, v0
	v_add_u32_e32 v2, 0x24800, v2
	ds_read_b32 v2, v2
	s_cmp_lt_i32 s79, -3
	s_waitcnt lgkmcnt(0)
	v_readfirstlane_b32 s0, v2
	s_cbranch_scc1 .LBB0_1659
	v_mbcnt_lo_u32_b32 v0, -1, v0
	v_mbcnt_hi_u32_b32 v12, -1, v0
	v_lshl_add_u32 v0, s0, 6, v12
	s_add_i32 s1, 0, 0x11200
	v_ashrrev_i32_e32 v13, 3, v0
	v_mov_b64_e32 v[2:3], s[74:75]
	v_lshlrev_b32_e32 v0, 4, v12
	v_lshl_add_u32 v124, v98, 4, s1
	ds_read2_b32 v[224:225], v124 offset1:1
	ds_read_b32 v231, v124 offset:8
	ds_read_b32 v237, v124 offset:12
	v_mad_i64_i32 v[2:3], s[0:1], v13, s89, v[2:3]
	v_and_b32_e32 v0, 0x70, v0
	v_lshl_add_u64 v[2:3], v[2:3], 0, v[0:1]
	global_load_dwordx4 v[6:9], v[2:3], off offset:3968
	s_nop 0
	global_load_dwordx4 v[2:5], v[2:3], off offset:3840
	v_bfe_u32 v14, v12, 2, 2
	v_lshrrev_b32_e32 v15, 3, v12
	v_and_b32_e32 v11, 31, v12
	v_and_or_b32 v14, v15, 4, v14
	v_bfe_u32 v10, v12, 5, 1
	v_mul_u32_u24_e32 v126, 0x90, v11
	v_and_b32_e32 v11, 16, v12
	v_mul_u32_u24_e32 v128, 0x90, v14
	v_lshlrev_b32_e32 v14, 2, v12
	v_lshlrev_b32_e32 v127, 4, v10
	v_lshlrev_b32_e32 v10, 2, v10
	v_and_or_b32 v11, v14, 12, v11
	v_lshlrev_b32_e32 v129, 1, v11
	v_or_b32_e32 v11, s21, v10
	v_cmp_gt_i32_e64 s[0:1], v10, v98
	v_cmp_lt_i32_e64 s[4:5], v10, v98
	v_or_b32_e32 v10, 33, v11
	v_cmp_gt_i32_e64 s[6:7], v10, v188
	v_or_b32_e32 v10, 2, v11
	v_cmp_gt_i32_e64 s[8:9], v10, v188
	v_or_b32_e32 v10, 34, v11
	v_cmp_gt_i32_e64 s[10:11], v10, v188
	v_or_b32_e32 v10, 3, v11
	v_cmp_gt_i32_e64 s[12:13], v10, v188
	v_or_b32_e32 v10, 35, v11
	v_cmp_gt_i32_e64 s[14:15], v10, v188
	v_or_b32_e32 v10, 8, v11
	v_cmp_gt_i32_e64 s[16:17], v10, v188
	v_or_b32_e32 v10, 40, v11
	v_cmp_gt_i32_e64 s[18:19], v10, v188
	v_or_b32_e32 v10, 9, v11
	v_cmp_gt_i32_e64 s[20:21], v10, v188
	v_or_b32_e32 v10, 41, v11
	v_mul_lo_u32 v125, v13, s23
	v_cmp_gt_i32_e64 s[22:23], v10, v188
	v_or_b32_e32 v10, 10, v11
	v_cmp_gt_i32_e64 s[24:25], v10, v188
	v_or_b32_e32 v10, 42, v11
	v_cmp_gt_i32_e64 s[26:27], v10, v188
	v_or_b32_e32 v10, 11, v11
	v_cmp_gt_i32_e64 s[28:29], v10, v188
	v_or_b32_e32 v10, 43, v11
	s_mov_b64 s[72:73], s[30:31]
	v_cmp_gt_i32_e64 s[30:31], v10, v188
	v_or_b32_e32 v10, 16, v11
	v_writelane_b32 v255, s36, 3
	v_cmp_gt_i32_e64 s[34:35], v10, v188
	v_or_b32_e32 v10, 48, v11
	v_writelane_b32 v255, s37, 4
	v_cmp_gt_i32_e64 s[36:37], v10, v188
	v_or_b32_e32 v10, 17, v11
	v_cmp_gt_i32_e64 s[38:39], v10, v188
	v_or_b32_e32 v10, 49, v11
	v_cmp_gt_i32_e64 s[40:41], v10, v188
	v_or_b32_e32 v10, 18, v11
	v_cmp_gt_i32_e64 s[42:43], v10, v188
	v_or_b32_e32 v10, 50, v11
	v_cmp_gt_i32_e64 s[44:45], v10, v188
	v_or_b32_e32 v10, 19, v11
	v_cmp_gt_i32_e64 s[46:47], v10, v188
	v_or_b32_e32 v10, 51, v11
	s_mov_b32 s83, s48
	v_cmp_gt_i32_e64 s[48:49], v10, v188
	v_or_b32_e32 v10, 24, v11
	v_cmp_gt_i32_e64 s[50:51], v10, v188
	v_or_b32_e32 v10, 56, v11
	v_cmp_gt_i32_e64 s[52:53], v10, v188
	v_or_b32_e32 v10, 25, v11
	v_cmp_gt_i32_e64 s[54:55], v10, v188
	v_or_b32_e32 v10, 57, v11
	v_cmp_gt_i32_e64 s[56:57], v10, v188
	v_or_b32_e32 v10, 26, v11
	v_cmp_gt_i32_e64 s[58:59], v10, v188
	v_or_b32_e32 v10, 58, v11
	v_cmp_gt_i32_e64 s[60:61], v10, v188
	v_or_b32_e32 v10, 27, v11
	v_cmp_gt_i32_e64 s[62:63], v10, v188
	v_or_b32_e32 v10, 59, v11
	v_or_b32_e32 v14, 32, v11
	v_cmp_gt_i32_e64 s[64:65], v10, v188
	v_mov_b64_e32 v[10:11], s[94:95]
	v_and_b32_e32 v12, 7, v12
	v_mad_i64_i32 v[10:11], s[80:81], v13, s89, v[10:11]
	v_lshlrev_b32_e32 v12, 4, v12
	v_mov_b32_e32 v13, v1
	v_lshl_add_u64 v[10:11], v[10:11], 0, v[12:13]
	v_mov_b32_e32 v62, v1
	v_mov_b32_e32 v63, v1
	v_lshl_add_u64 v[10:11], s[66:67], 0, v[10:11]
	s_mov_b64 s[66:67], 0xaa58f80
	v_mov_b32_e32 v48, v1
	v_mov_b32_e32 v49, v1
	v_mov_b32_e32 v50, v1
	v_mov_b32_e32 v51, v1
	v_mov_b32_e32 v52, v1
	v_mov_b32_e32 v53, v1
	v_mov_b32_e32 v54, v1
	v_mov_b32_e32 v55, v1
	v_mov_b32_e32 v56, v1
	v_mov_b32_e32 v57, v1
	v_mov_b32_e32 v58, v1
	v_mov_b32_e32 v59, v1
	v_mov_b32_e32 v60, v1
	v_mov_b32_e32 v61, v1
	v_mov_b64_e32 v[78:79], v[62:63]
	s_mov_b32 s82, 0x40c00000
	v_cmp_gt_i32_e64 s[2:3], v14, v188
	v_lshl_add_u64 v[14:15], v[10:11], 0, s[66:67]
	s_add_i32 s79, s79, 4
	s_mov_b32 s80, 0
	v_mov_b32_e32 v194, 0
	v_mov_b64_e32 v[76:77], v[60:61]
	v_mov_b64_e32 v[74:75], v[58:59]
	v_mov_b64_e32 v[72:73], v[56:57]
	v_mov_b64_e32 v[70:71], v[54:55]
	v_mov_b64_e32 v[68:69], v[52:53]
	v_mov_b64_e32 v[66:67], v[50:51]
	v_mov_b64_e32 v[64:65], v[48:49]
	v_mov_b32_e32 v130, 0
	s_branch .LBB0_1652

.LBB0_1654:
	s_lshr_b32 s66, s80, 5
	v_mov_b32_e32 v10, v224
	s_cmp_eq_u32 s66, 0
	s_cbranch_scc1 .Lbm_done
	v_mov_b32_e32 v10, v225
	s_cmp_eq_u32 s66, 1
	s_cbranch_scc1 .Lbm_done
	v_mov_b32_e32 v10, v231
	s_cmp_eq_u32 s66, 2
	s_cbranch_scc1 .Lbm_done
	v_mov_b32_e32 v10, v237
.Lbm_done:
	s_and_b32 s66, s80, 31
	v_lshrrev_b32_e32 v11, s80, v10
	v_bfe_u32 v10, v10, s66, 1
	v_and_b32_e32 v11, 1, v11
	v_cmp_ne_u32_e32 vcc, 0, v10
	v_cmp_eq_u32_e64 s[66:67], 1, v11
	s_cbranch_vccz .LBB0_1651
	v_add3_u32 v112, s81, v126, v127
	ds_read_b128 v[10:13], v112
	ds_read_b128 v[220:223], v112 offset:4608
	ds_read_b128 v[240:243], v112 offset:32
	ds_read_b128 v[244:247], v112 offset:4640
	ds_read_b128 v[248:251], v112 offset:64
	v_cndmask_b32_e64 v80, v236, -v130, s[66:67]
	v_mov_b32_e32 v81, v80
	v_mov_b32_e32 v82, v80
	v_mov_b32_e32 v83, v80
	v_mov_b32_e32 v84, v80
	v_mov_b32_e32 v85, v80
	v_mov_b32_e32 v86, v80
	v_mov_b32_e32 v87, v80
	v_mov_b32_e32 v88, v80
	v_mov_b32_e32 v89, v80
	v_mov_b32_e32 v90, v80
	v_mov_b32_e32 v91, v80
	v_mov_b32_e32 v92, v80
	v_mov_b32_e32 v93, v80
	v_mov_b32_e32 v94, v80
	v_mov_b32_e32 v95, v80
	s_cmp_lg_u32 s76, s80
	s_waitcnt lgkmcnt(4)
	v_mfma_f32_32x32x16_bf16 v[96:111], v[10:13], v[144:147], v[80:95]
	ds_read_b128 v[10:13], v112 offset:4672
	s_waitcnt lgkmcnt(4)
	v_mfma_f32_32x32x16_bf16 v[80:95], v[220:223], v[144:147], v[80:95]
	ds_read_b128 v[220:223], v112 offset:96
	s_waitcnt lgkmcnt(4)
	v_mfma_f32_32x32x16_bf16 v[96:111], v[240:243], v[148:151], v[96:111]
	ds_read_b128 v[240:243], v112 offset:4704
	s_waitcnt lgkmcnt(4)
	v_mfma_f32_32x32x16_bf16 v[80:95], v[244:247], v[148:151], v[80:95]
	s_waitcnt lgkmcnt(3)
	v_mfma_f32_32x32x16_bf16 v[96:111], v[248:251], v[152:155], v[96:111]
	s_waitcnt lgkmcnt(2)
	v_mfma_f32_32x32x16_bf16 v[80:95], v[10:13], v[152:155], v[80:95]
	s_waitcnt lgkmcnt(1)
	v_mfma_f32_32x32x16_bf16 v[96:111], v[220:223], v[156:159], v[96:111]
	s_waitcnt lgkmcnt(0)
	v_mfma_f32_32x32x16_bf16 v[80:95], v[240:243], v[156:159], v[80:95]
	s_cbranch_scc1 .LBB0_1657
	s_nop 7
	v_cndmask_b32_e64 v10, v96, v236, s[0:1]
	s_nop 1
	v_cndmask_b32_e64 v80, v80, v236, s[2:3]
	v_cndmask_b32_e64 v97, v236, v97, s[4:5]
	v_cndmask_b32_e64 v96, v10, v96, s[4:5]
	v_cndmask_b32_e64 v81, v81, v236, s[6:7]
	v_cndmask_b32_e64 v98, v98, v236, s[8:9]
	v_cndmask_b32_e64 v82, v82, v236, s[10:11]
	v_cndmask_b32_e64 v99, v99, v236, s[12:13]
	v_cndmask_b32_e64 v83, v83, v236, s[14:15]
	v_cndmask_b32_e64 v100, v100, v236, s[16:17]
	v_cndmask_b32_e64 v84, v84, v236, s[18:19]
	v_cndmask_b32_e64 v101, v101, v236, s[20:21]
	v_cndmask_b32_e64 v85, v85, v236, s[22:23]
	v_cndmask_b32_e64 v102, v102, v236, s[24:25]
	v_cndmask_b32_e64 v86, v86, v236, s[26:27]
	v_cndmask_b32_e64 v103, v103, v236, s[28:29]
	v_cndmask_b32_e64 v87, v87, v236, s[30:31]
	v_cndmask_b32_e64 v104, v104, v236, s[34:35]
	v_cndmask_b32_e64 v88, v88, v236, s[36:37]
	v_cndmask_b32_e64 v105, v105, v236, s[38:39]
	v_cndmask_b32_e64 v89, v89, v236, s[40:41]
	v_cndmask_b32_e64 v106, v106, v236, s[42:43]
	v_cndmask_b32_e64 v90, v90, v236, s[44:45]
	v_cndmask_b32_e64 v107, v107, v236, s[46:47]
	v_cndmask_b32_e64 v91, v91, v236, s[48:49]
	v_cndmask_b32_e64 v108, v108, v236, s[50:51]
	v_cndmask_b32_e64 v92, v92, v236, s[52:53]
	v_cndmask_b32_e64 v109, v109, v236, s[54:55]
	v_cndmask_b32_e64 v93, v93, v236, s[56:57]
	v_cndmask_b32_e64 v110, v110, v236, s[58:59]
	v_cndmask_b32_e64 v94, v94, v236, s[60:61]
	v_cndmask_b32_e64 v111, v111, v236, s[62:63]
	v_cndmask_b32_e64 v95, v95, v236, s[64:65]
